# plus flogit: 32 operand loads issued up front, 16 MFMAs behind counted waits
# speedup vs baseline: 1.0161x; 1.0056x over previous
; __device__ __forceinline__ void flogit_prestep(const Frame& F, const bf16* XN, const bf16* WF, const float* xs, const float* bfv, float* logf) {
;     ...
;     for (int base = F.vcu; base < M / 16; base += F.G * 4) { const int task = base + F.G * tw; const bool valid = task < M / 16;
;         const int r0 = 16 * (128 * ((task >> 5) & 7) + (task & 31) + 32 * (task >> 8));
;         f32x4 acc = (f32x4){0.f, 0.f, 0.f, 0.f};
;         if (valid) { const bf16* ap = XN + (size_t)(r0 + fr) * D + 8 * fq + 512 * half; const bf16* bp = WF + (size_t)fr * D + 8 * fq + 512 * half;
; #pragma unroll 8
;             for (int ks = 0; ks < 16; ++ks) { const bf16x8 a = *(const bf16x8*)(ap + 32 * ks), b = *(const bf16x8*)(bp + 32 * ks); acc = __builtin_amdgcn_mfma_f32_16x16x32_bf16(a, b, acc, 0, 0, 0); } }
.LBB0_198:
	global_load_dwordx4 v[42:45], v[4:5], off offset:-256
	global_load_dwordx4 v[116:119], v[20:21], off offset:-256
	global_load_dwordx4 v[46:49], v[4:5], off offset:-192
	global_load_dwordx4 v[120:123], v[20:21], off offset:-192
	global_load_dwordx4 v[50:53], v[4:5], off offset:-128
	global_load_dwordx4 v[124:127], v[20:21], off offset:-128
	global_load_dwordx4 v[54:57], v[4:5], off offset:-64
	global_load_dwordx4 v[128:131], v[20:21], off offset:-64
	global_load_dwordx4 v[58:61], v[4:5], off
	global_load_dwordx4 v[132:135], v[20:21], off
	global_load_dwordx4 v[62:65], v[4:5], off offset:64
	global_load_dwordx4 v[136:139], v[20:21], off offset:64
	global_load_dwordx4 v[66:69], v[4:5], off offset:128
	global_load_dwordx4 v[140:143], v[20:21], off offset:128
	global_load_dwordx4 v[70:73], v[4:5], off offset:192
	global_load_dwordx4 v[144:147], v[20:21], off offset:192
	s_mov_b64 s[6:7], 0x200
	v_lshl_add_u64 v[14:15], v[4:5], 0, s[6:7]
	v_lshl_add_u64 v[24:25], v[20:21], 0, s[6:7]
	global_load_dwordx4 v[74:77], v[14:15], off offset:-256
	global_load_dwordx4 v[148:151], v[24:25], off offset:-256
	global_load_dwordx4 v[78:81], v[14:15], off offset:-192
	global_load_dwordx4 v[152:155], v[24:25], off offset:-192
	global_load_dwordx4 v[82:85], v[14:15], off offset:-128
	global_load_dwordx4 v[156:159], v[24:25], off offset:-128
	global_load_dwordx4 v[86:89], v[14:15], off offset:-64
	global_load_dwordx4 v[160:163], v[24:25], off offset:-64
	global_load_dwordx4 v[90:93], v[14:15], off
	global_load_dwordx4 v[164:167], v[24:25], off
	global_load_dwordx4 v[94:97], v[14:15], off offset:64
	global_load_dwordx4 v[168:171], v[24:25], off offset:64
	global_load_dwordx4 v[98:101], v[14:15], off offset:128
	global_load_dwordx4 v[172:175], v[24:25], off offset:128
	global_load_dwordx4 v[102:105], v[14:15], off offset:192
	global_load_dwordx4 v[176:179], v[24:25], off offset:192
	s_waitcnt vmcnt(30)
	v_mfma_f32_16x16x32_bf16 v[0:3], v[42:45], v[116:119], v[0:3]
	s_waitcnt vmcnt(28)
	v_mfma_f32_16x16x32_bf16 v[0:3], v[46:49], v[120:123], v[0:3]
	s_waitcnt vmcnt(26)
	v_mfma_f32_16x16x32_bf16 v[0:3], v[50:53], v[124:127], v[0:3]
	s_waitcnt vmcnt(24)
	v_mfma_f32_16x16x32_bf16 v[0:3], v[54:57], v[128:131], v[0:3]
	s_waitcnt vmcnt(22)
	v_mfma_f32_16x16x32_bf16 v[0:3], v[58:61], v[132:135], v[0:3]
	s_waitcnt vmcnt(20)
	v_mfma_f32_16x16x32_bf16 v[0:3], v[62:65], v[136:139], v[0:3]
	s_waitcnt vmcnt(18)
	v_mfma_f32_16x16x32_bf16 v[0:3], v[66:69], v[140:143], v[0:3]
	s_waitcnt vmcnt(16)
	v_mfma_f32_16x16x32_bf16 v[0:3], v[70:73], v[144:147], v[0:3]
	s_waitcnt vmcnt(14)
	v_mfma_f32_16x16x32_bf16 v[0:3], v[74:77], v[148:151], v[0:3]
	s_waitcnt vmcnt(12)
	v_mfma_f32_16x16x32_bf16 v[0:3], v[78:81], v[152:155], v[0:3]
	s_waitcnt vmcnt(10)
	v_mfma_f32_16x16x32_bf16 v[0:3], v[82:85], v[156:159], v[0:3]
	s_waitcnt vmcnt(8)
	v_mfma_f32_16x16x32_bf16 v[0:3], v[86:89], v[160:163], v[0:3]
	s_waitcnt vmcnt(6)
	v_mfma_f32_16x16x32_bf16 v[0:3], v[90:93], v[164:167], v[0:3]
	s_waitcnt vmcnt(4)
	v_mfma_f32_16x16x32_bf16 v[0:3], v[94:97], v[168:171], v[0:3]
	s_waitcnt vmcnt(2)
	v_mfma_f32_16x16x32_bf16 v[0:3], v[98:101], v[172:175], v[0:3]
	s_waitcnt vmcnt(0)
	v_mfma_f32_16x16x32_bf16 v[0:3], v[102:105], v[176:179], v[0:3]
